# speedup vs baseline: 1.0217x; 1.0217x over previous
; DI int get_bid() { int b = blockIdx.x; asm volatile("" : "+s"(b)); return b; }
; DI int get_tid_(int wv) { int z = 0; asm volatile("" : "+v"(z)); asm volatile("" : "+s"(wv)); const int lane = __builtin_amdgcn_mbcnt_hi(~0u, __builtin_amdgcn_mbcnt_lo(~0u, z)); return (wv << 6) | lane; }
; #define RW_LOAD(r_) do { _Pragma("unroll") for (int j = 0; j < 4; ++j) { xn[j] = *(const f32x4*)(xsrc + ((size_t)b * S_ + (r_)) * 1024 + j * 256 + lane * 4); \
;         if (has_post) tn[j] = *(const u32x2*)(p.proj + (size_t)(r_) * LDP + j * 256 + lane * 4); } } while (0)
; DI void rowwise(const PP& p, int l, int b, int mode, char* lds) {
;     const int tid = get_tid_(p.wv), wid = tid >> 6, lane = tid & 63;
;     const bool has_post = mode != 0, has_pre = mode != 3, has_ff = (mode == 0 || mode == 2);
;     const int lp = (mode == 2) ? l - 1 : l;
;     const float* gate = p.mod + ((size_t)(lp * 2 + b) * 6 + (mode == 1 ? 2 : 5)) * 1024;
;     const float* gpost = (mode == 1 ? p.g_post_mix : p.g_post_mlp) + lp * 1024;
;     const float* gpre = (mode == 1 ? p.g_pre_mlp : p.g_pre_mix) + l * 1024;
;     const float* shp = p.mod + ((size_t)(l * 2 + b) * 6 + (mode == 1 ? 3 : 0)) * 1024;
;     const float* scp = shp + 1024;
;     const float* xsrc = (mode == 0 || (mode == 1 && l == 0)) ? p.x : p.out;
;     float* wl = (float*)lds;
;     __syncthreads();
;     if (has_ff) {
; #pragma unroll
;         for (int i = 0; i < 4; ++i) *(f32x4*)(wl + (tid + 512 * i) * 4) = *(const f32x4*)(p.wff + (size_t)l * 8192 + (tid + 512 * i) * 4);
;     }
;     __syncthreads();
;     const int row0 = get_bid() * 8 + wid, rstride = gridDim.x * 8;
;     f32x4 xn[4]; u32x2 tn[4];
;     ...
;     if (row0 < S_) RW_LOAD(row0);
;     for (int row = row0; row < S_; row += rstride) {
;         const size_t tok = (size_t)b * S_ + row;
;         f32x4 xv[4]; u32x2 tw[4];
; #pragma unroll
;         for (int j = 0; j < 4; ++j) { xv[j] = xn[j]; tw[j] = tn[j]; }
;         if (row + rstride < S_) RW_LOAD(row + rstride);
.LBB0_95:
	s_cmp_gt_i32 s29, 5
	s_mov_b64 s[0:1], -1
	s_cbranch_scc0 .LBB0_102
	v_mov_b32_e32 v0, v1
	s_mov_b32 s0, s64
	v_mbcnt_lo_u32_b32 v0, -1, v0
	v_mbcnt_hi_u32_b32 v2, -1, v0
	v_lshl_or_b32 v0, s0, 6, v2
	v_readlane_b32 s0, v253, 0
	v_ashrrev_i32_e32 v0, 6, v0
	s_barrier
	s_barrier
	s_nop 0
	v_lshl_add_u32 v38, s0, 3, v0
	s_movk_i32 s0, 0x4000
	v_cmp_gt_i32_e32 vcc, s0, v38
	s_and_saveexec_b64 s[2:3], vcc
	s_cbranch_execz .LBB0_101
	s_load_dword s30, s[24:25], 0x0
	v_readlane_b32 s48, v253, 3
	s_mov_b64 vcc, s[2:3]
	v_readlane_b32 s49, v253, 4
	v_readlane_b32 s50, v253, 5
	s_waitcnt lgkmcnt(0)
	s_lshl_b32 s92, s30, 3
	s_and_b64 s[0:1], s[90:91], exec
	v_readlane_b32 s0, v254, 34
	v_readlane_b32 s51, v253, 6
	v_readlane_b32 s52, v253, 7
	v_readlane_b32 s53, v253, 8
	v_readlane_b32 s54, v253, 9
	v_readlane_b32 s55, v253, 10
	v_readlane_b32 s14, v254, 48
	v_readlane_b32 s15, v254, 49
	s_cselect_b32 s0, 2, 0
	v_readlane_b32 s1, v254, 35
	s_cselect_b32 s22, s15, s49
	s_cselect_b32 s24, s14, s48
	s_add_i32 s0, s0, s94
	v_readlane_b32 s40, v254, 50
	v_readlane_b32 s10, v254, 44
	s_mul_hi_i32 s1, s0, 0x6000
	s_mulk_i32 s0, 0x6000
	v_readlane_b32 s41, v254, 51
	v_readlane_b32 s42, v254, 52
	v_readlane_b32 s43, v254, 53
	v_readlane_b32 s44, v254, 54
	v_readlane_b32 s45, v254, 55
	v_readlane_b32 s46, v254, 56
	v_readlane_b32 s47, v254, 57
	v_readlane_b32 s48, v254, 58
	v_readlane_b32 s49, v254, 59
	v_readlane_b32 s50, v254, 60
	v_readlane_b32 s51, v254, 61
	v_readlane_b32 s52, v254, 62
	v_readlane_b32 s53, v254, 63
	v_readlane_b32 s54, v255, 0
	v_readlane_b32 s55, v255, 1
	s_add_u32 s10, s42, s0
	v_readlane_b32 s40, v254, 50
	v_readlane_b32 s11, v254, 45
	v_readlane_b32 s43, v254, 53
	v_readlane_b32 s8, v254, 42
	s_addc_u32 s11, s43, s1
	v_readlane_b32 s9, v254, 43
	s_add_u32 s8, s10, 0x3000
	v_readlane_b32 s12, v254, 46
	s_addc_u32 s9, s11, 0
	v_readlane_b32 s13, v254, 47
	s_add_u32 s12, s10, 0x4000
	s_addc_u32 s13, s11, 0
	s_and_b64 s[0:1], s[90:91], exec
	v_readlane_b32 s60, v253, 15
	s_cselect_b32 s0, 0x1000, 0
	v_readlane_b32 s61, v253, 16
	s_add_u32 s14, s60, s0
	v_readlane_b32 s58, v253, 13
	s_addc_u32 s15, s61, 0
	v_readlane_b32 s59, v253, 14
	s_add_u32 s18, s58, s0
	s_addc_u32 s19, s59, 0
	s_add_u32 s16, s10, 0x2000
	s_addc_u32 s17, s11, 0
	s_ashr_i32 s95, s94, 31
	s_lshl_b64 s[10:11], s[94:95], 26
	v_ashrrev_i32_e32 v39, 31, v38
	s_add_u32 s0, s24, s10
	v_lshlrev_b32_e32 v0, 2, v2
	s_addc_u32 s1, s22, s11
	v_lshlrev_b64 v[4:5], 12, v[38:39]
	v_and_b32_e32 v3, 0xfc, v0
	v_lshl_add_u64 v[6:7], s[0:1], 0, v[4:5]
	v_lshlrev_b32_e32 v0, 2, v3
	v_mov_b64_e32 v[8:9], s[86:87]
	v_lshl_add_u64 v[6:7], v[6:7], 0, v[0:1]
	v_mad_i64_i32 v[10:11], s[24:25], v38, s35, v[8:9]
	v_lshlrev_b32_e32 v12, 1, v3
	v_mov_b32_e32 v13, v1
	v_lshl_add_u64 v[10:11], v[10:11], 0, v[12:13]
	global_load_dwordx4 v[30:33], v[6:7], off
	global_load_dwordx2 v[88:89], v[10:11], off
	global_load_dwordx4 v[26:29], v[6:7], off offset:1024
	global_load_dwordx2 v[86:87], v[10:11], off offset:512
	global_load_dwordx4 v[18:21], v[6:7], off offset:2048
	global_load_dwordx2 v[36:37], v[10:11], off offset:1024
	global_load_dwordx4 v[22:25], v[6:7], off offset:3072
	global_load_dwordx2 v[34:35], v[10:11], off offset:1536
	v_readlane_b32 s41, v254, 51
	v_readlane_b32 s42, v254, 52
	v_readlane_b32 s44, v254, 54
	v_readlane_b32 s45, v254, 55
	v_readlane_b32 s46, v254, 56
	v_readlane_b32 s47, v254, 57
	v_readlane_b32 s48, v254, 58
	v_readlane_b32 s49, v254, 59
	v_readlane_b32 s50, v254, 60
	v_readlane_b32 s51, v254, 61
	v_or_b32_e32 v6, 0x400, v0
	v_mov_b32_e32 v7, v1
	v_lshl_add_u64 v[44:45], s[16:17], 0, v[6:7]
	v_lshl_add_u64 v[56:57], s[12:13], 0, v[6:7]
	v_lshl_add_u64 v[58:59], s[8:9], 0, v[6:7]
	v_and_b32_e32 v6, 63, v2
	v_add_u32_e32 v2, s92, v38
	v_readlane_b32 s36, v254, 34
	v_readlane_b32 s56, v253, 11
	v_readlane_b32 s57, v253, 12
	v_readlane_b32 s62, v253, 17
	v_readlane_b32 s63, v253, 18
	v_readlane_b32 s2, v254, 36
	v_readlane_b32 s52, v254, 62
	v_readlane_b32 s53, v254, 63
	v_readlane_b32 s54, v255, 0
	v_readlane_b32 s55, v255, 1
	v_or_b32_e32 v10, 0x800, v0
	v_mov_b32_e32 v11, v1
	v_or_b32_e32 v12, 0xc00, v0
	v_ashrrev_i32_e32 v3, 31, v2
	s_ashr_i32 s93, s92, 31
	v_readlane_b32 s50, v254, 48
	s_mov_b32 s2, s64
	v_readlane_b32 s52, v254, 50
	v_lshl_add_u64 v[54:55], s[8:9], 0, v[0:1]
	v_lshl_add_u64 v[62:63], s[8:9], 0, v[10:11]
	v_lshl_add_u64 v[66:67], s[8:9], 0, v[12:13]
	v_mad_i64_i32 v[68:69], s[8:9], v2, s35, v[8:9]
	v_readlane_b32 s51, v254, 49
	s_add_u32 s10, s50, s10
	v_lshlrev_b64 v[2:3], 12, v[2:3]
	v_readlane_b32 s3, v254, 37
	v_readlane_b32 s4, v254, 38
	v_readlane_b32 s5, v254, 39
	v_readlane_b32 s53, v254, 51
	v_readlane_b32 s54, v254, 52
	v_readlane_b32 s55, v254, 53
	v_readlane_b32 s56, v254, 54
	v_readlane_b32 s57, v254, 55
	v_readlane_b32 s58, v254, 56
	v_readlane_b32 s59, v254, 57
	v_readlane_b32 s60, v254, 58
	v_readlane_b32 s61, v254, 59
	v_readlane_b32 s62, v254, 60
	v_readlane_b32 s63, v254, 61
	v_readlane_b32 s48, v254, 46
	v_readlane_b32 s49, v254, 47
	s_addc_u32 s11, s51, s11
	v_lshl_add_u64 v[74:75], s[0:1], 0, v[2:3]
	v_lshlrev_b64 v[2:3], 11, v[38:39]
	v_readlane_b32 s5, v255, 4
	v_readlane_b32 s4, v255, 3
	v_readlane_b32 s3, v255, 2
	v_readlane_b32 s64, v254, 62
	v_readlane_b32 s65, v254, 63
	v_readlane_b32 s66, v255, 0
	v_readlane_b32 s67, v255, 1
	v_readlane_b32 s24, v255, 6
	v_lshl_add_u64 v[40:41], s[16:17], 0, v[0:1]
	v_lshl_add_u64 v[42:43], s[18:19], 0, v[0:1]
	v_lshl_add_u64 v[46:47], s[16:17], 0, v[10:11]
	v_lshl_add_u64 v[48:49], s[16:17], 0, v[12:13]
	v_lshl_add_u64 v[50:51], s[14:15], 0, v[0:1]
	v_lshl_add_u64 v[52:53], s[12:13], 0, v[0:1]
	v_lshl_add_u64 v[60:61], s[12:13], 0, v[10:11]
	v_lshl_add_u64 v[64:65], s[12:13], 0, v[12:13]
	v_lshlrev_b32_e32 v0, 3, v6
	v_lshlrev_b32_e32 v70, 4, v6
	v_readlane_b32 s44, v254, 42
	v_readlane_b32 s45, v254, 43
	v_readlane_b32 s47, v254, 45
	s_mov_b64 s[48:49], s[52:53]
	v_lshl_add_u64 v[72:73], s[10:11], 0, v[4:5]
	v_lshl_add_u64 v[76:77], s[84:85], 0, v[2:3]
	s_waitcnt vmcnt(7)
; DI float bflo(unsigned w) { return __uint_as_float(w << 16); }
; DI float bfhi(unsigned w) { return __uint_as_float(w & 0xffff0000u); }
; #define RW_LOAD(r_) do { _Pragma("unroll") for (int j = 0; j < 4; ++j) { xn[j] = *(const f32x4*)(xsrc + ((size_t)b * S_ + (r_)) * 1024 + j * 256 + lane * 4); \
;         if (has_post) tn[j] = *(const u32x2*)(p.proj + (size_t)(r_) * LDP + j * 256 + lane * 4); } } while (0)
; DI void rowwise(const PP& p, int l, int b, int mode, char* lds) {
;     ...
;     for (int row = row0; row < S_; row += rstride) {
;         const size_t tok = (size_t)b * S_ + row;
;         f32x4 xv[4]; u32x2 tw[4];
; #pragma unroll
;         for (int j = 0; j < 4; ++j) { xv[j] = xn[j]; tw[j] = tn[j]; }
;         if (row + rstride < S_) RW_LOAD(row + rstride);
;         if (has_post) {
;             f32x4 tv[4]; float ss = 0.f;
; #pragma unroll
;             for (int j = 0; j < 4; ++j) {
;                 const u32x2 w = tw[j];
;                 tv[j] = (f32x4){bflo(w.x), bfhi(w.x), bflo(w.y), bfhi(w.y)};
;                 ss += tv[j][0] * tv[j][0] + tv[j][1] * tv[j][1] + tv[j][2] * tv[j][2] + tv[j][3] * tv[j][3];
;             }
;             ss = wave_sum(ss);
;             const float rstd = rsqrtf(ss * (1.f / 1024.f) + 1e-6f);
; #pragma unroll
;             for (int j = 0; j < 4; ++j) {
;                 const int c = j * 256 + lane * 4;
;                 const f32x4 g = *(const f32x4*)(gate + c), gp = *(const f32x4*)(gpost + c);
;                 xv[j] += g * (tv[j] * rstd * gp);
;                 *(f32x4*)(p.out + tok * 1024 + c) = xv[j];
;             }
	v_mov_b64_e32 v[2:3], v[30:31]
	s_waitcnt vmcnt(5)
	v_mov_b64_e32 v[6:7], v[26:27]
	s_waitcnt vmcnt(3)
	v_mov_b64_e32 v[10:11], v[18:19]
	s_waitcnt vmcnt(1)
	v_mov_b64_e32 v[14:15], v[22:23]
	s_brev_b32 s28, 1
	v_readlane_b32 s25, v255, 7
	s_mul_i32 s8, s30, 0x2c000
	s_mov_b64 s[30:31], 0
	s_mul_hi_i32 s9, s92, 0x5800
	v_mov_b32_e32 v71, v1
	s_mov_b32 s45, s5
	s_mov_b32 s44, s4
	s_mov_b32 s47, s3
	s_mov_b64 s[50:51], s[54:55]
	s_mov_b64 s[52:53], s[56:57]
	s_mov_b64 s[54:55], s[58:59]
	s_mov_b64 s[56:57], s[60:61]
	s_mov_b64 s[58:59], s[62:63]
	s_mov_b64 s[60:61], s[64:65]
	s_mov_b64 s[62:63], s[66:67]
	s_mov_b32 s66, 0x800000
	s_mov_b32 s64, s2
	s_mov_b64 s[2:3], vcc
	s_lshl_b64 s[10:11], s[92:93], 12
	s_lshl_b64 s[12:13], s[92:93], 11
	s_mov_b64 s[14:15], 0
	v_mov_b64_e32 v[78:79], v[88:89]
	v_mov_b64_e32 v[80:81], v[86:87]
	v_mov_b64_e32 v[82:83], v[36:37]
	s_waitcnt vmcnt(0)
	v_mov_b64_e32 v[84:85], v[34:35]
	v_mov_b64_e32 v[4:5], v[32:33]
	v_mov_b64_e32 v[8:9], v[28:29]
	v_mov_b64_e32 v[12:13], v[20:21]
	v_mov_b64_e32 v[16:17], v[24:25]
	v_readlane_b32 s6, v254, 40
	v_readlane_b32 s7, v254, 41
	v_readlane_b32 s37, v254, 35
	v_readlane_b32 s38, v254, 36
	v_readlane_b32 s39, v254, 37
	v_readlane_b32 s40, v254, 38
	v_readlane_b32 s41, v254, 39
	v_readlane_b32 s42, v254, 40
	v_readlane_b32 s43, v254, 41
	v_readlane_b32 s46, v254, 44
	global_load_dwordx4 v[108:111], v[40:41], off
	global_load_dwordx4 v[112:115], v[44:45], off
	global_load_dwordx4 v[116:119], v[46:47], off
	global_load_dwordx4 v[120:123], v[48:49], off
	global_load_dwordx4 v[124:127], v[42:43], off
	global_load_dwordx4 v[128:131], v[42:43], off offset:1024
	global_load_dwordx4 v[132:135], v[42:43], off offset:2048
	global_load_dwordx4 v[136:139], v[42:43], off offset:3072
	global_load_dwordx4 v[140:143], v[50:51], off
	global_load_dwordx4 v[144:147], v[50:51], off offset:1024
	global_load_dwordx4 v[148:151], v[50:51], off offset:2048
	global_load_dwordx4 v[152:155], v[50:51], off offset:3072
	global_load_dwordx4 v[156:159], v[52:53], off
	global_load_dwordx4 v[160:163], v[56:57], off
	global_load_dwordx4 v[164:167], v[60:61], off
	global_load_dwordx4 v[168:171], v[64:65], off
	global_load_dwordx4 v[172:175], v[54:55], off
	global_load_dwordx4 v[176:179], v[58:59], off
	global_load_dwordx4 v[180:183], v[62:63], off
	global_load_dwordx4 v[184:187], v[66:67], off
	s_waitcnt vmcnt(0)
	s_branch .LBB0_99
.LBB0_98:
	s_or_b64 exec, exec, s[16:17]
	v_and_b32_e32 v101, 0xffff0000, v88
	v_and_b32_e32 v97, 0xffff0000, v86
	v_lshlrev_b32_e32 v100, 16, v88
	v_mul_f32_e32 v39, v101, v101
	v_lshlrev_b32_e32 v96, 16, v86
	v_mul_f32_e32 v86, v97, v97
	v_lshlrev_b32_e32 v102, 16, v89
	v_fmac_f32_e32 v39, v100, v100
	v_lshlrev_b32_e32 v98, 16, v87
	v_fmac_f32_e32 v86, v96, v96
	v_and_b32_e32 v103, 0xffff0000, v89
	v_fmac_f32_e32 v39, v102, v102
	v_and_b32_e32 v99, 0xffff0000, v87
	v_fmac_f32_e32 v86, v98, v98
	v_and_b32_e32 v91, 0xffff0000, v36
	v_fmac_f32_e32 v39, v103, v103
	v_fmac_f32_e32 v86, v99, v99
	v_lshlrev_b32_e32 v90, 16, v36
	v_mul_f32_e32 v36, v91, v91
	v_and_b32_e32 v87, 0xffff0000, v34
	v_add_f32_e32 v39, v39, v86
	v_lshlrev_b32_e32 v94, 16, v37
	v_fmac_f32_e32 v36, v90, v90
	v_lshlrev_b32_e32 v86, 16, v34
	v_mul_f32_e32 v34, v87, v87
	v_and_b32_e32 v95, 0xffff0000, v37
	v_fmac_f32_e32 v36, v94, v94
	v_lshlrev_b32_e32 v88, 16, v35
	v_fmac_f32_e32 v34, v86, v86
	v_fmac_f32_e32 v36, v95, v95
	v_and_b32_e32 v89, 0xffff0000, v35
	v_fmac_f32_e32 v34, v88, v88
	v_add_f32_e32 v36, v39, v36
	v_fmac_f32_e32 v34, v89, v89
	v_add_f32_e32 v34, v36, v34
	s_and_b64 s[0:1], exec, vcc
	s_or_b64 s[14:15], s[0:1], s[14:15]
	v_add_f32_dpp v34, v34, v34 quad_perm:[1,0,3,2] row_mask:0xf bank_mask:0xf bound_ctrl:1
	v_lshl_add_u64 v[68:69], v[68:69], 0, s[8:9]
	v_lshl_add_u64 v[74:75], v[74:75], 0, s[10:11]
	v_add_f32_dpp v34, v34, v34 quad_perm:[2,3,0,1] row_mask:0xf bank_mask:0xf bound_ctrl:1
	ds_swizzle_b32 v35, v34 offset:swizzle(SWAP,4)
	s_waitcnt lgkmcnt(0)
	v_add_f32_e32 v34, v34, v35
	ds_swizzle_b32 v35, v34 offset:swizzle(SWAP,8)
	s_waitcnt lgkmcnt(0)
	v_add_f32_e32 v34, v34, v35
	ds_swizzle_b32 v35, v34 offset:swizzle(SWAP,16)
	s_waitcnt lgkmcnt(0)
	v_add_f32_e32 v34, v34, v35
	v_mov_b32_e32 v35, v34
	s_nop 1
	v_permlane32_swap_b32_e32 v34, v35
	v_add_f32_e32 v34, v34, v35
	v_fmamk_f32 v34, v34, 0x3a800000, v217
	v_cmp_gt_f32_e32 vcc, s66, v34
	v_mul_f32_e32 v35, 0x4b800000, v34
	s_nop 0
	v_cndmask_b32_e32 v34, v34, v35, vcc
	v_rsq_f32_e32 v34, v34
	s_nop 0
	v_mul_f32_e32 v35, 0x45800000, v34
	v_cndmask_b32_e32 v92, v34, v35, vcc
	v_pk_mul_f32 v[102:103], v[102:103], v[92:93] op_sel_hi:[1,0]
	v_pk_mul_f32 v[100:101], v[100:101], v[92:93] op_sel_hi:[1,0]
	v_pk_mul_f32 v[98:99], v[98:99], v[92:93] op_sel_hi:[1,0]
	v_pk_mul_f32 v[96:97], v[96:97], v[92:93] op_sel_hi:[1,0]
	v_pk_mul_f32 v[94:95], v[94:95], v[92:93] op_sel_hi:[1,0]
	v_pk_mul_f32 v[90:91], v[90:91], v[92:93] op_sel_hi:[1,0]
	v_pk_mul_f32 v[88:89], v[88:89], v[92:93] op_sel_hi:[1,0]
	v_pk_mul_f32 v[86:87], v[86:87], v[92:93] op_sel_hi:[1,0]
	v_mov_b64_e32 v[34:35], v[108:109]
	v_mov_b64_e32 v[36:37], v[110:111]
	v_mov_b64_e32 v[104:105], v[124:125]
	v_mov_b64_e32 v[106:107], v[126:127]
	v_pk_mul_f32 v[100:101], v[104:105], v[100:101]
	v_pk_mul_f32 v[102:103], v[106:107], v[102:103]
	v_pk_fma_f32 v[30:31], v[34:35], v[100:101], v[30:31]
	v_pk_fma_f32 v[32:33], v[36:37], v[102:103], v[32:33]
	v_lshl_add_u64 v[104:105], v[72:73], 0, v[70:71]
	global_store_dwordx4 v[104:105], v[30:33], off
	v_lshl_add_u64 v[72:73], v[72:73], 0, s[10:11]
	v_mov_b64_e32 v[34:35], v[112:113]
	v_mov_b64_e32 v[36:37], v[114:115]
	v_mov_b64_e32 v[100:101], v[128:129]
; DI float bflo(unsigned w) { return __uint_as_float(w << 16); }
; DI float bfhi(unsigned w) { return __uint_as_float(w & 0xffff0000u); }
; DI unsigned cvtpk(float lo, float hi) { unsigned r; asm volatile("v_cvt_pk_bf16_f32 %0, %1, %2" : "=v"(r) : "v"(lo), "v"(hi)); return r; }
; DI void rowwise(const PP& p, int l, int b, int mode, char* lds) {
;     ...
;             f32x4 tv[4]; float ss = 0.f;
; #pragma unroll
;             for (int j = 0; j < 4; ++j) {
;                 const u32x2 w = tw[j];
;                 tv[j] = (f32x4){bflo(w.x), bfhi(w.x), bflo(w.y), bfhi(w.y)};
;                 ss += tv[j][0] * tv[j][0] + tv[j][1] * tv[j][1] + tv[j][2] * tv[j][2] + tv[j][3] * tv[j][3];
;             }
;             ss = wave_sum(ss);
;             const float rstd = rsqrtf(ss * (1.f / 1024.f) + 1e-6f);
; #pragma unroll
;             for (int j = 0; j < 4; ++j) {
;                 const int c = j * 256 + lane * 4;
;                 const f32x4 g = *(const f32x4*)(gate + c), gp = *(const f32x4*)(gpost + c);
;                 xv[j] += g * (tv[j] * rstd * gp);
;                 *(f32x4*)(p.out + tok * 1024 + c) = xv[j];
;             }
;         }
;         if (has_pre) {
;             float ss = 0.f;
; #pragma unroll
;             for (int j = 0; j < 4; ++j) ss += xv[j][0] * xv[j][0] + xv[j][1] * xv[j][1] + xv[j][2] * xv[j][2] + xv[j][3] * xv[j][3];
;             ss = wave_sum(ss);
;             const float rstd = rsqrtf(ss * (1.f / 1024.f) + 1e-6f);
;             f32x4 hv[4];
; #pragma unroll
;             for (int j = 0; j < 4; ++j) {
;                 const int c = j * 256 + lane * 4;
;                 const f32x4 g = *(const f32x4*)(gpre + c), sc = *(const f32x4*)(scp + c), sh = *(const f32x4*)(shp + c);
;                 hv[j] = xv[j] * rstd * g * (1.f + sc) + sh;
;                 u32x2 w = {cvtpk(hv[j][0], hv[j][1]), cvtpk(hv[j][2], hv[j][3])};
;                 *(u32x2*)(p.h + (size_t)row * 1024 + c) = w;
;             }
	v_mov_b64_e32 v[102:103], v[130:131]
	v_pk_mul_f32 v[96:97], v[100:101], v[96:97]
	v_pk_mul_f32 v[98:99], v[102:103], v[98:99]
	v_pk_fma_f32 v[26:27], v[34:35], v[96:97], v[26:27]
	v_pk_fma_f32 v[28:29], v[36:37], v[98:99], v[28:29]
	global_store_dwordx4 v[104:105], v[26:29], off offset:1024
	v_mov_b64_e32 v[34:35], v[116:117]
	v_mov_b64_e32 v[36:37], v[118:119]
	v_mov_b64_e32 v[96:97], v[132:133]
	v_mov_b64_e32 v[98:99], v[134:135]
	v_pk_mul_f32 v[90:91], v[96:97], v[90:91]
	v_pk_mul_f32 v[94:95], v[98:99], v[94:95]
	v_pk_fma_f32 v[18:19], v[34:35], v[90:91], v[18:19]
	v_pk_fma_f32 v[20:21], v[36:37], v[94:95], v[20:21]
	global_store_dwordx4 v[104:105], v[18:21], off offset:2048
	v_mov_b64_e32 v[34:35], v[120:121]
	v_mov_b64_e32 v[36:37], v[122:123]
	v_mov_b64_e32 v[94:95], v[136:137]
	v_mov_b64_e32 v[96:97], v[138:139]
	v_pk_mul_f32 v[86:87], v[94:95], v[86:87]
	v_pk_mul_f32 v[88:89], v[96:97], v[88:89]
	v_pk_fma_f32 v[22:23], v[34:35], v[86:87], v[22:23]
	v_pk_fma_f32 v[24:25], v[36:37], v[88:89], v[24:25]
	global_store_dwordx4 v[104:105], v[22:25], off offset:3072
	v_mul_f32_e32 v34, v31, v31
	v_mul_f32_e32 v35, v27, v27
	v_fmac_f32_e32 v34, v30, v30
	v_fmac_f32_e32 v35, v26, v26
	v_fmac_f32_e32 v34, v32, v32
	v_fmac_f32_e32 v35, v28, v28
	v_fmac_f32_e32 v34, v33, v33
	v_fmac_f32_e32 v35, v29, v29
	v_add_f32_e32 v34, v34, v35
	v_mul_f32_e32 v35, v19, v19
	v_fmac_f32_e32 v35, v18, v18
	v_fmac_f32_e32 v35, v20, v20
	v_fmac_f32_e32 v35, v21, v21
	v_add_f32_e32 v34, v35, v34
	v_mul_f32_e32 v35, v23, v23
	v_fmac_f32_e32 v35, v22, v22
	v_fmac_f32_e32 v35, v24, v24
	v_fmac_f32_e32 v35, v25, v25
	v_add_f32_e32 v34, v35, v34
	v_mov_b64_e32 v[86:87], v[140:141]
	v_mov_b64_e32 v[88:89], v[142:143]
	v_mov_b64_e32 v[90:91], v[156:157]
	v_mov_b64_e32 v[92:93], v[158:159]
	v_pk_add_f32 v[36:37], v[92:93], 1.0 op_sel_hi:[1,0]
	v_add_f32_dpp v34, v34, v34 quad_perm:[1,0,3,2] row_mask:0xf bank_mask:0xf bound_ctrl:1
	s_nop 1
	v_add_f32_dpp v34, v34, v34 quad_perm:[2,3,0,1] row_mask:0xf bank_mask:0xf bound_ctrl:1
	ds_swizzle_b32 v35, v34 offset:swizzle(SWAP,4)
	s_waitcnt lgkmcnt(0)
	v_add_f32_e32 v34, v34, v35
	ds_swizzle_b32 v35, v34 offset:swizzle(SWAP,8)
	s_waitcnt lgkmcnt(0)
	v_add_f32_e32 v34, v34, v35
	ds_swizzle_b32 v35, v34 offset:swizzle(SWAP,16)
	s_waitcnt lgkmcnt(0)
	v_add_f32_e32 v34, v34, v35
	v_mov_b32_e32 v35, v34
	s_nop 1
	v_permlane32_swap_b32_e32 v34, v35
	v_add_f32_e32 v34, v34, v35
	v_fmamk_f32 v34, v34, 0x3a800000, v217
	v_cmp_gt_f32_e32 vcc, s66, v34
	v_mul_f32_e32 v35, 0x4b800000, v34
	s_nop 0
	v_cndmask_b32_e32 v34, v34, v35, vcc
	v_rsq_f32_e32 v34, v34
	s_nop 0
	v_mul_f32_e32 v35, 0x45800000, v34
	v_cndmask_b32_e32 v34, v34, v35, vcc
	v_pk_mul_f32 v[32:33], v[32:33], v[34:35] op_sel_hi:[1,0]
	v_pk_mul_f32 v[30:31], v[30:31], v[34:35] op_sel_hi:[1,0]
	v_pk_mul_f32 v[32:33], v[88:89], v[32:33]
	v_pk_mul_f32 v[30:31], v[86:87], v[30:31]
	v_pk_add_f32 v[86:87], v[90:91], 1.0 op_sel_hi:[1,0]
	v_mov_b64_e32 v[94:95], v[172:173]
	v_mov_b64_e32 v[96:97], v[174:175]
	v_pk_fma_f32 v[32:33], v[36:37], v[32:33], v[96:97]
	v_pk_fma_f32 v[30:31], v[86:87], v[30:31], v[94:95]
	v_lshl_add_u64 v[36:37], v[76:77], 0, v[0:1]
	v_cvt_pk_bf16_f32 v30, v30, v31
	v_cvt_pk_bf16_f32 v31, v32, v33
	global_store_dwordx2 v[36:37], v[30:31], off
	s_nop 0
	v_pk_mul_f32 v[28:29], v[28:29], v[34:35] op_sel_hi:[1,0]
	v_pk_mul_f32 v[26:27], v[26:27], v[34:35] op_sel_hi:[1,0]
	v_pk_mul_f32 v[20:21], v[20:21], v[34:35] op_sel_hi:[1,0]
	v_pk_mul_f32 v[18:19], v[18:19], v[34:35] op_sel_hi:[1,0]
	v_pk_mul_f32 v[24:25], v[24:25], v[34:35] op_sel_hi:[1,0]
	v_pk_mul_f32 v[22:23], v[22:23], v[34:35] op_sel_hi:[1,0]
	v_lshl_add_u64 v[76:77], v[76:77], 0, s[12:13]
	s_waitcnt vmcnt(0)
	v_mov_b64_e32 v[34:35], v[84:85]
	v_mov_b64_e32 v[30:31], v[144:145]
	v_mov_b64_e32 v[32:33], v[146:147]
	v_pk_mul_f32 v[26:27], v[30:31], v[26:27]
	v_pk_mul_f32 v[28:29], v[32:33], v[28:29]
	v_mov_b64_e32 v[86:87], v[160:161]
	v_mov_b64_e32 v[88:89], v[162:163]
	v_pk_add_f32 v[32:33], v[86:87], 1.0 op_sel_hi:[1,0]
	v_pk_add_f32 v[30:31], v[88:89], 1.0 op_sel_hi:[1,0]
	v_mov_b64_e32 v[90:91], v[176:177]
	v_mov_b64_e32 v[92:93], v[178:179]
	v_pk_fma_f32 v[26:27], v[32:33], v[26:27], v[90:91]
	v_pk_fma_f32 v[28:29], v[30:31], v[28:29], v[92:93]
	v_cvt_pk_bf16_f32 v26, v26, v27
	s_nop 0
	v_cvt_pk_bf16_f32 v27, v28, v29
	global_store_dwordx2 v[36:37], v[26:27], off offset:512
	s_nop 0
	v_mov_b64_e32 v[26:27], v[148:149]
	v_mov_b64_e32 v[28:29], v[150:151]
	v_pk_mul_f32 v[18:19], v[18:19], v[26:27]
	v_pk_mul_f32 v[20:21], v[20:21], v[28:29]
	v_mov_b64_e32 v[30:31], v[164:165]
	v_mov_b64_e32 v[32:33], v[166:167]
	v_pk_add_f32 v[28:29], v[30:31], 1.0 op_sel_hi:[1,0]
	v_pk_add_f32 v[26:27], v[32:33], 1.0 op_sel_hi:[1,0]
	v_mov_b64_e32 v[86:87], v[180:181]
	v_mov_b64_e32 v[88:89], v[182:183]
	v_pk_fma_f32 v[18:19], v[18:19], v[28:29], v[86:87]
	v_pk_fma_f32 v[20:21], v[20:21], v[26:27], v[88:89]
	v_cvt_pk_bf16_f32 v18, v18, v19
	v_mov_b64_e32 v[88:89], v[78:79]
	v_cvt_pk_bf16_f32 v19, v20, v21
	global_store_dwordx2 v[36:37], v[18:19], off offset:1024
	s_nop 0
	v_mov_b64_e32 v[86:87], v[80:81]
	v_mov_b64_e32 v[18:19], v[152:153]
	v_mov_b64_e32 v[20:21], v[154:155]
	v_pk_mul_f32 v[18:19], v[22:23], v[18:19]
	v_pk_mul_f32 v[20:21], v[24:25], v[20:21]
	v_mov_b64_e32 v[26:27], v[168:169]
	v_mov_b64_e32 v[28:29], v[170:171]
	v_pk_add_f32 v[24:25], v[26:27], 1.0 op_sel_hi:[1,0]
	v_pk_add_f32 v[22:23], v[28:29], 1.0 op_sel_hi:[1,0]
	v_mov_b64_e32 v[30:31], v[184:185]
	v_mov_b64_e32 v[32:33], v[186:187]
	v_pk_fma_f32 v[18:19], v[18:19], v[24:25], v[30:31]
	v_pk_fma_f32 v[20:21], v[20:21], v[22:23], v[32:33]
	v_cvt_pk_bf16_f32 v18, v18, v19
	v_mov_b64_e32 v[32:33], v[4:5]
	v_cvt_pk_bf16_f32 v19, v20, v21
	global_store_dwordx2 v[36:37], v[18:19], off offset:1536
	v_mov_b64_e32 v[28:29], v[8:9]
	v_mov_b64_e32 v[20:21], v[12:13]
	v_mov_b64_e32 v[24:25], v[16:17]
	v_mov_b64_e32 v[36:37], v[82:83]
	v_mov_b64_e32 v[30:31], v[2:3]
	v_mov_b64_e32 v[26:27], v[6:7]
	v_mov_b64_e32 v[18:19], v[10:11]
	v_mov_b64_e32 v[22:23], v[14:15]
	s_andn2_b64 exec, exec, s[14:15]
	s_cbranch_execz .LBB0_101

; DI int get_bid() { int b = blockIdx.x; asm volatile("" : "+s"(b)); return b; }
; DI int get_tid_(int wv) { int z = 0; asm volatile("" : "+v"(z)); asm volatile("" : "+s"(wv)); const int lane = __builtin_amdgcn_mbcnt_hi(~0u, __builtin_amdgcn_mbcnt_lo(~0u, z)); return (wv << 6) | lane; }
; #define RW_LOAD(r_) do { _Pragma("unroll") for (int j = 0; j < 4; ++j) { xn[j] = *(const f32x4*)(xsrc + ((size_t)b * S_ + (r_)) * 1024 + j * 256 + lane * 4); \
;         if (has_post) tn[j] = *(const u32x2*)(p.proj + (size_t)(r_) * LDP + j * 256 + lane * 4); } } while (0)
; DI void rowwise(const PP& p, int l, int b, int mode, char* lds) {
;     const int tid = get_tid_(p.wv), wid = tid >> 6, lane = tid & 63;
;     const bool has_post = mode != 0, has_pre = mode != 3, has_ff = (mode == 0 || mode == 2);
;     const int lp = (mode == 2) ? l - 1 : l;
;     const float* gate = p.mod + ((size_t)(lp * 2 + b) * 6 + (mode == 1 ? 2 : 5)) * 1024;
;     const float* gpost = (mode == 1 ? p.g_post_mix : p.g_post_mlp) + lp * 1024;
;     const float* gpre = (mode == 1 ? p.g_pre_mlp : p.g_pre_mix) + l * 1024;
;     const float* shp = p.mod + ((size_t)(l * 2 + b) * 6 + (mode == 1 ? 3 : 0)) * 1024;
;     const float* scp = shp + 1024;
;     const float* xsrc = (mode == 0 || (mode == 1 && l == 0)) ? p.x : p.out;
;     float* wl = (float*)lds;
;     __syncthreads();
;     if (has_ff) {
; #pragma unroll
;         for (int i = 0; i < 4; ++i) *(f32x4*)(wl + (tid + 512 * i) * 4) = *(const f32x4*)(p.wff + (size_t)l * 8192 + (tid + 512 * i) * 4);
;     }
;     __syncthreads();
;     const int row0 = get_bid() * 8 + wid, rstride = gridDim.x * 8;
;     f32x4 xn[4]; u32x2 tn[4];
;     ...
;     if (row0 < S_) RW_LOAD(row0);
.LBB0_409:
	s_mul_i32 s6, s14, 0x6000
	s_mul_hi_i32 s4, s14, 0x6000
	s_add_u32 s6, s54, s6
	s_addc_u32 s4, s55, s4
	s_add_u32 s6, s6, 0x5000
	s_addc_u32 s7, s4, 0
	s_and_b64 s[8:9], s[12:13], exec
	v_readlane_b32 s48, v253, 3
	s_cselect_b32 s4, 0x1000, 0
	v_readlane_b32 s56, v253, 11
	v_readlane_b32 s57, v253, 12
	s_add_u32 s8, s56, s4
	s_addc_u32 s9, s57, 0
	s_and_b64 s[12:13], s[12:13], exec
	v_readlane_b32 s49, v253, 4
	v_readlane_b32 s50, v253, 5
	v_readlane_b32 s51, v253, 6
	v_readlane_b32 s52, v253, 7
	v_readlane_b32 s53, v253, 8
	v_readlane_b32 s54, v253, 9
	v_readlane_b32 s55, v253, 10
	s_cselect_b32 s4, 2, 0
	s_add_i32 s4, s4, s14
	v_readlane_b32 s40, v254, 50
	s_load_dword s16, s[24:25], 0x0
	s_mul_hi_i32 s13, s4, 0x6000
	s_mulk_i32 s4, 0x6000
	v_readlane_b32 s41, v254, 51
	v_readlane_b32 s42, v254, 52
	v_readlane_b32 s43, v254, 53
	v_readlane_b32 s44, v254, 54
	v_readlane_b32 s45, v254, 55
	v_readlane_b32 s46, v254, 56
	v_readlane_b32 s47, v254, 57
	v_readlane_b32 s48, v254, 58
	v_readlane_b32 s49, v254, 59
	v_readlane_b32 s50, v254, 60
	v_readlane_b32 s51, v254, 61
	v_readlane_b32 s52, v254, 62
	v_readlane_b32 s53, v254, 63
	v_readlane_b32 s54, v255, 0
	v_readlane_b32 s55, v255, 1
	s_add_u32 s12, s42, s4
	v_readlane_b32 s40, v254, 50
	v_readlane_b32 s43, v254, 53
	s_addc_u32 s13, s43, s13
	v_readlane_b32 s58, v253, 13
	v_readlane_b32 s59, v253, 14
	s_mov_b32 s94, s14
	v_readlane_b32 s44, v254, 54
	v_readlane_b32 s45, v254, 55
	v_readlane_b32 s46, v254, 56
	v_readlane_b32 s47, v254, 57
	v_readlane_b32 s48, v254, 58
	v_readlane_b32 s49, v254, 59
	v_readlane_b32 s50, v254, 60
	v_readlane_b32 s51, v254, 61
	v_readlane_b32 s52, v254, 62
	v_readlane_b32 s53, v254, 63
	v_readlane_b32 s54, v255, 0
	v_readlane_b32 s55, v255, 1
	s_add_u32 s14, s12, 0x1000
	v_lshlrev_b32_e32 v12, 2, v9
	s_addc_u32 s15, s13, 0
	s_waitcnt lgkmcnt(0)
	s_lshl_b32 s4, s16, 3
	v_and_b32_e32 v4, 16, v8
	v_lshrrev_b32_e32 v14, 3, v9
	v_readlane_b32 s44, v254, 34
	v_or_b32_e32 v15, s5, v14
	v_cmp_eq_u32_e64 s[38:39], 0, v4
	v_lshlrev_b32_e32 v4, 2, v12
	v_mov_b32_e32 v5, v1
	v_readlane_b32 s58, v254, 48
	s_ashr_i32 s5, s4, 31
	v_readlane_b32 s62, v253, 17
	v_readlane_b32 s63, v253, 18
	v_or_b32_e32 v37, 0x200, v12
	v_lshl_add_u64 v[46:47], s[8:9], 0, v[4:5]
	v_readlane_b32 s59, v254, 49
	s_add_u32 s8, s58, s0
	v_lshl_add_u64 v[38:39], s[6:7], 0, v[4:5]
	v_lshlrev_b32_e32 v10, 2, v37
	v_mov_b32_e32 v11, v1
	v_or_b32_e32 v60, 0x300, v12
	v_lshl_add_u64 v[48:49], s[62:63], 0, v[4:5]
	v_lshl_add_u64 v[50:51], s[14:15], 0, v[4:5]
	v_lshl_add_u64 v[52:53], s[12:13], 0, v[4:5]
	v_lshlrev_b32_e32 v4, 2, v15
	v_readlane_b32 s45, v254, 35
	s_addc_u32 s9, s59, s1
	v_or_b32_e32 v17, 0x100, v12
	v_lshl_add_u64 v[42:43], s[6:7], 0, v[10:11]
	v_lshlrev_b32_e32 v12, 2, v60
	v_lshl_add_u64 v[56:57], s[14:15], 0, v[10:11]
	v_lshlrev_b32_e32 v11, 5, v60
	v_lshl_add_u64 v[60:61], s[44:45], 0, v[4:5]
	v_add_u32_e32 v4, s4, v34
	v_lshl_add_u64 v[64:65], s[8:9], 0, v[2:3]
	s_lshl_b64 s[8:9], s[4:5], 12
	v_ashrrev_i32_e32 v5, 31, v4
	s_add_u32 s0, s11, s0
	v_readlane_b32 s60, v253, 15
	v_readlane_b32 s61, v253, 16
	v_readlane_b32 s48, v254, 38
	v_readlane_b32 s49, v254, 39
	v_readlane_b32 s50, v254, 40
	v_readlane_b32 s51, v254, 41
	v_readlane_b32 s52, v254, 42
	v_readlane_b32 s53, v254, 43
	v_readlane_b32 s54, v254, 44
	v_readlane_b32 s55, v254, 45
	v_readlane_b32 s56, v254, 46
	v_readlane_b32 s57, v254, 47
	v_lshlrev_b64 v[2:3], 12, v[4:5]
	s_addc_u32 s1, s10, s1
	v_readlane_b32 s72, v255, 8
	v_readlane_b32 s48, v254, 50
	v_lshl_add_u64 v[66:67], s[0:1], 0, v[2:3]
	v_lshlrev_b64 v[2:3], 5, v[34:35]
	v_readlane_b32 s42, v254, 52
	v_and_b32_e32 v16, 8, v8
	v_lshlrev_b32_e32 v6, 2, v17
	v_mov_b32_e32 v7, v1
	v_and_b32_e32 v8, 7, v8
	v_readlane_b32 s86, v255, 22
	v_readlane_b32 s87, v255, 23
	v_readlane_b32 s58, v254, 60
	v_readlane_b32 s59, v254, 61
	v_lshl_or_b32 v2, v14, 2, v2
	v_readlane_b32 s41, v254, 51
	v_lshl_add_u64 v[40:41], s[6:7], 0, v[6:7]
	v_mov_b32_e32 v13, v1
	v_cmp_eq_u32_e64 s[42:43], 0, v8
	v_lshl_add_u64 v[54:55], s[14:15], 0, v[6:7]
	v_lshlrev_b32_e32 v8, 7, v9
	v_lshlrev_b32_e32 v9, 5, v17
	v_lshlrev_b32_e32 v10, 5, v37
	v_readlane_b32 s84, v255, 20
	v_readlane_b32 s85, v255, 21
	v_mov_b64_e32 v[6:7], s[86:87]
	v_lshl_add_u64 v[68:69], s[58:59], 0, v[2:3]
	v_lshlrev_b64 v[2:3], 11, v[34:35]
	v_lshl_add_u64 v[44:45], s[6:7], 0, v[12:13]
	v_cmp_eq_u32_e64 s[40:41], 0, v16
	v_lshl_add_u64 v[58:59], s[14:15], 0, v[12:13]
	v_readlane_b32 s47, v254, 37
	v_mad_i64_i32 v[62:63], s[6:7], v4, s35, v[6:7]
	v_lshl_add_u64 v[70:71], s[84:85], 0, v[2:3]
	v_add_u32_e32 v35, 0, v8
	v_add_u32_e32 v90, 0, v9
	v_add_u32_e32 v91, 0, v10
	v_add_u32_e32 v92, 0, v11
	s_waitcnt vmcnt(0)
; DI int get_bid() { int b = blockIdx.x; asm volatile("" : "+s"(b)); return b; }
; #define RW_LOAD(r_) do { _Pragma("unroll") for (int j = 0; j < 4; ++j) { xn[j] = *(const f32x4*)(xsrc + ((size_t)b * S_ + (r_)) * 1024 + j * 256 + lane * 4); \
;         if (has_post) tn[j] = *(const u32x2*)(p.proj + (size_t)(r_) * LDP + j * 256 + lane * 4); } } while (0)
; DI void rowwise(const PP& p, int l, int b, int mode, char* lds) {
;     ...
;     const int row0 = get_bid() * 8 + wid, rstride = gridDim.x * 8;
;     f32x4 xn[4]; u32x2 tn[4];
;     ...
;     if (row0 < S_) RW_LOAD(row0);
;     for (int row = row0; row < S_; row += rstride) {
;         const size_t tok = (size_t)b * S_ + row;
;         f32x4 xv[4]; u32x2 tw[4];
; #pragma unroll
;         for (int j = 0; j < 4; ++j) { xv[j] = xn[j]; tw[j] = tn[j]; }
;         if (row + rstride < S_) RW_LOAD(row + rstride);
	v_mov_b64_e32 v[14:15], v[18:19]
	v_mov_b64_e32 v[10:11], v[22:23]
	v_mov_b64_e32 v[6:7], v[26:27]
	v_mov_b64_e32 v[2:3], v[30:31]
	v_readlane_b32 s73, v255, 9
	v_readlane_b32 s74, v255, 10
	v_readlane_b32 s75, v255, 11
	v_readlane_b32 s76, v255, 12
	v_readlane_b32 s77, v255, 13
	v_readlane_b32 s78, v255, 14
	v_readlane_b32 s79, v255, 15
	v_readlane_b32 s80, v255, 16
	v_readlane_b32 s81, v255, 17
	v_readlane_b32 s82, v255, 18
	v_readlane_b32 s83, v255, 19
	s_mul_i32 s6, s16, 0x2c000
	s_mul_hi_i32 s7, s4, 0x5800
	v_mov_b32_e32 v37, v1
	v_readlane_b32 s49, v254, 51
	v_readlane_b32 s50, v254, 52
	v_readlane_b32 s51, v254, 53
	v_readlane_b32 s52, v254, 54
	v_readlane_b32 s53, v254, 55
	v_readlane_b32 s54, v254, 56
	v_readlane_b32 s55, v254, 57
	v_readlane_b32 s56, v254, 58
	v_readlane_b32 s57, v254, 59
	v_readlane_b32 s60, v254, 62
	v_readlane_b32 s61, v254, 63
	v_readlane_b32 s62, v255, 0
	v_readlane_b32 s63, v255, 1
	s_lshl_b64 s[10:11], s[4:5], 5
	s_lshl_b64 s[12:13], s[4:5], 11
	v_mov_b64_e32 v[16:17], v[20:21]
	v_mov_b64_e32 v[12:13], v[24:25]
	v_mov_b64_e32 v[8:9], v[28:29]
	v_mov_b64_e32 v[4:5], v[32:33]
	v_mov_b64_e32 v[78:79], v[86:87]
	v_mov_b64_e32 v[76:77], v[84:85]
	v_mov_b64_e32 v[74:75], v[82:83]
	v_mov_b64_e32 v[72:73], v[80:81]
	s_mov_b64 s[14:15], 0
	v_readlane_b32 s47, v255, 2
	v_readlane_b32 s44, v255, 3
	v_readlane_b32 s45, v255, 4
	s_brev_b32 s28, 1
	v_readlane_b32 s46, v254, 36
	global_load_dwordx4 v[118:121], v[48:49], off
	global_load_dwordx4 v[122:125], v[38:39], off
	global_load_dwordx4 v[126:129], v[48:49], off offset:1024
	global_load_dwordx4 v[130:133], v[40:41], off
	global_load_dwordx4 v[134:137], v[48:49], off offset:2048
	global_load_dwordx4 v[138:141], v[42:43], off
	global_load_dwordx4 v[142:145], v[48:49], off offset:3072
	global_load_dwordx4 v[150:153], v[44:45], off
	global_load_dwordx4 v[158:161], v[46:47], off
	global_load_dwordx4 v[162:165], v[50:51], off
	global_load_dwordx4 v[166:169], v[52:53], off
	global_load_dwordx4 v[170:173], v[46:47], off offset:1024
	global_load_dwordx4 v[174:177], v[54:55], off
	global_load_dwordx4 v[178:181], v[52:53], off offset:1024
	global_load_dwordx4 v[182:185], v[46:47], off offset:2048
	global_load_dwordx4 v[186:189], v[56:57], off
	global_load_dwordx4 v[190:193], v[52:53], off offset:2048
	global_load_dwordx4 v[194:197], v[46:47], off offset:3072
	global_load_dwordx4 v[198:201], v[58:59], off
	global_load_dwordx4 v[202:205], v[52:53], off offset:3072
	global_load_dword v146, v[60:61], off
	s_waitcnt vmcnt(0)
	s_branch .LBB0_411
.LBB0_410:
	s_or_b64 exec, exec, s[16:17]
	s_waitcnt vmcnt(0)
	v_mov_b64_e32 v[32:33], v[4:5]
	v_mov_b64_e32 v[28:29], v[8:9]
	v_mov_b64_e32 v[24:25], v[12:13]
	v_mov_b64_e32 v[20:21], v[16:17]
	v_lshl_add_u64 v[62:63], v[62:63], 0, s[6:7]
	v_lshl_add_u64 v[64:65], v[64:65], 0, s[8:9]
	v_lshl_add_u64 v[66:67], v[66:67], 0, s[8:9]
	v_lshl_add_u64 v[68:69], v[68:69], 0, s[10:11]
	v_lshl_add_u64 v[70:71], v[70:71], 0, s[12:13]
	v_mov_b64_e32 v[80:81], v[72:73]
	v_mov_b64_e32 v[82:83], v[74:75]
	v_mov_b64_e32 v[84:85], v[76:77]
	v_mov_b64_e32 v[86:87], v[78:79]
	v_mov_b64_e32 v[30:31], v[2:3]
	v_mov_b64_e32 v[26:27], v[6:7]
	v_mov_b64_e32 v[22:23], v[10:11]
	v_mov_b64_e32 v[18:19], v[14:15]
	s_andn2_b64 exec, exec, s[14:15]
	s_cbranch_execz .LBB0_425

; DI float bflo(unsigned w) { return __uint_as_float(w << 16); }
; DI float bfhi(unsigned w) { return __uint_as_float(w & 0xffff0000u); }
; DI void rowwise(const PP& p, int l, int b, int mode, char* lds) {
;     ...
;         if (has_post) {
;             f32x4 tv[4]; float ss = 0.f;
; #pragma unroll
;             for (int j = 0; j < 4; ++j) {
;                 const u32x2 w = tw[j];
;                 tv[j] = (f32x4){bflo(w.x), bfhi(w.x), bflo(w.y), bfhi(w.y)};
;                 ss += tv[j][0] * tv[j][0] + tv[j][1] * tv[j][1] + tv[j][2] * tv[j][2] + tv[j][3] * tv[j][3];
;             }
;             ss = wave_sum(ss);
;             const float rstd = rsqrtf(ss * (1.f / 1024.f) + 1e-6f);
; #pragma unroll
;             for (int j = 0; j < 4; ++j) {
;                 const int c = j * 256 + lane * 4;
;                 const f32x4 g = *(const f32x4*)(gate + c), gp = *(const f32x4*)(gpost + c);
;                 xv[j] += g * (tv[j] * rstd * gp);
;                 *(f32x4*)(p.out + tok * 1024 + c) = xv[j];
;             }
.LBB0_417:
	s_or_b64 exec, exec, s[16:17]
	s_and_b64 s[0:1], exec, s[0:1]
	s_or_b64 s[14:15], s[0:1], s[14:15]
	s_and_b64 vcc, exec, s[36:37]
	s_cbranch_vccnz .LBB0_419
	v_and_b32_e32 v89, 0xffff0000, v80
	v_and_b32_e32 v103, 0xffff0000, v82
	v_lshlrev_b32_e32 v88, 16, v80
	v_lshlrev_b32_e32 v102, 16, v82
	v_lshlrev_b32_e32 v104, 16, v83
	v_and_b32_e32 v105, 0xffff0000, v83
	v_and_b32_e32 v107, 0xffff0000, v84
	v_mul_f32_e32 v82, v89, v89
	v_mul_f32_e32 v83, v103, v103
	v_lshlrev_b32_e32 v80, 16, v81
	v_lshlrev_b32_e32 v106, 16, v84
	v_and_b32_e32 v111, 0xffff0000, v86
	v_mul_f32_e32 v84, v107, v107
	v_fmac_f32_e32 v82, v88, v88
	v_fmac_f32_e32 v83, v102, v102
	v_and_b32_e32 v81, 0xffff0000, v81
	v_lshlrev_b32_e32 v108, 16, v85
	v_and_b32_e32 v109, 0xffff0000, v85
	v_lshlrev_b32_e32 v110, 16, v86
	v_mul_f32_e32 v85, v111, v111
	v_fmac_f32_e32 v84, v106, v106
	v_fmac_f32_e32 v82, v80, v80
	v_fmac_f32_e32 v83, v104, v104
	v_lshlrev_b32_e32 v112, 16, v87
	v_fmac_f32_e32 v85, v110, v110
	v_fmac_f32_e32 v84, v108, v108
	v_fmac_f32_e32 v82, v81, v81
	v_fmac_f32_e32 v83, v105, v105
	v_and_b32_e32 v113, 0xffff0000, v87
	v_fmac_f32_e32 v85, v112, v112
	v_fmac_f32_e32 v84, v109, v109
	v_add_f32_e32 v82, v82, v83
	v_fmac_f32_e32 v85, v113, v113
	v_add_f32_e32 v82, v82, v84
	v_add_f32_e32 v82, v82, v85
	v_lshl_add_u64 v[114:115], v[64:65], 0, v[36:37]
	s_nop 0
	v_add_f32_dpp v82, v82, v82 quad_perm:[1,0,3,2] row_mask:0xf bank_mask:0xf bound_ctrl:1
	s_nop 1
	v_add_f32_dpp v82, v82, v82 quad_perm:[2,3,0,1] row_mask:0xf bank_mask:0xf bound_ctrl:1
	ds_swizzle_b32 v83, v82 offset:swizzle(SWAP,4)
	s_waitcnt lgkmcnt(0)
	v_add_f32_e32 v82, v82, v83
	ds_swizzle_b32 v83, v82 offset:swizzle(SWAP,8)
	s_waitcnt lgkmcnt(0)
	v_add_f32_e32 v82, v82, v83
	ds_swizzle_b32 v83, v82 offset:swizzle(SWAP,16)
	s_waitcnt lgkmcnt(0)
	v_add_f32_e32 v82, v82, v83
	v_mov_b32_e32 v83, v82
	s_nop 1
	v_permlane32_swap_b32_e32 v82, v83
	v_add_f32_e32 v82, v82, v83
	v_fmamk_f32 v82, v82, 0x3a800000, v217
	v_mul_f32_e32 v83, 0x4b800000, v82
	v_cmp_gt_f32_e32 vcc, s66, v82
	s_nop 1
	v_cndmask_b32_e32 v82, v82, v83, vcc
	v_rsq_f32_e32 v82, v82
	s_nop 0
	v_mul_f32_e32 v83, 0x45800000, v82
	v_cndmask_b32_e32 v116, v82, v83, vcc
	v_pk_mul_f32 v[80:81], v[80:81], v[116:117] op_sel_hi:[1,0]
	v_pk_mul_f32 v[82:83], v[88:89], v[116:117] op_sel_hi:[1,0]
	v_pk_mul_f32 v[88:89], v[104:105], v[116:117] op_sel_hi:[1,0]
	v_mov_b64_e32 v[94:95], v[118:119]
	v_mov_b64_e32 v[96:97], v[120:121]
	v_pk_mul_f32 v[82:83], v[94:95], v[82:83]
	v_pk_mul_f32 v[80:81], v[96:97], v[80:81]
	v_mov_b64_e32 v[98:99], v[122:123]
	v_mov_b64_e32 v[100:101], v[124:125]
	v_pk_fma_f32 v[30:31], v[98:99], v[82:83], v[30:31]
	v_pk_fma_f32 v[32:33], v[100:101], v[80:81], v[32:33]
	global_store_dwordx4 v[114:115], v[30:33], off
	v_pk_mul_f32 v[94:95], v[102:103], v[116:117] op_sel_hi:[1,0]
	v_mov_b64_e32 v[80:81], v[126:127]
	v_mov_b64_e32 v[82:83], v[128:129]
	v_pk_mul_f32 v[82:83], v[82:83], v[88:89]
	v_pk_mul_f32 v[80:81], v[80:81], v[94:95]
	v_mov_b64_e32 v[84:85], v[130:131]
	v_mov_b64_e32 v[86:87], v[132:133]
	v_pk_fma_f32 v[28:29], v[86:87], v[82:83], v[28:29]
	v_pk_fma_f32 v[26:27], v[84:85], v[80:81], v[26:27]
	global_store_dwordx4 v[114:115], v[26:29], off offset:1024
	v_pk_mul_f32 v[88:89], v[108:109], v[116:117] op_sel_hi:[1,0]
	v_pk_mul_f32 v[94:95], v[106:107], v[116:117] op_sel_hi:[1,0]
	v_mov_b64_e32 v[80:81], v[134:135]
	v_mov_b64_e32 v[82:83], v[136:137]
	v_pk_mul_f32 v[82:83], v[82:83], v[88:89]
	v_pk_mul_f32 v[80:81], v[80:81], v[94:95]
	v_mov_b64_e32 v[84:85], v[138:139]
	v_mov_b64_e32 v[86:87], v[140:141]
	v_pk_fma_f32 v[24:25], v[86:87], v[82:83], v[24:25]
	v_pk_fma_f32 v[22:23], v[84:85], v[80:81], v[22:23]
	global_store_dwordx4 v[114:115], v[22:25], off offset:2048
	v_pk_mul_f32 v[88:89], v[112:113], v[116:117] op_sel_hi:[1,0]
	v_pk_mul_f32 v[94:95], v[110:111], v[116:117] op_sel_hi:[1,0]
	v_mov_b64_e32 v[80:81], v[142:143]
	v_mov_b64_e32 v[82:83], v[144:145]
	v_pk_mul_f32 v[82:83], v[82:83], v[88:89]
	v_pk_mul_f32 v[80:81], v[80:81], v[94:95]
	v_mov_b64_e32 v[84:85], v[150:151]
	v_mov_b64_e32 v[86:87], v[152:153]
	v_pk_fma_f32 v[20:21], v[86:87], v[82:83], v[20:21]
	v_pk_fma_f32 v[18:19], v[84:85], v[80:81], v[18:19]
	global_store_dwordx4 v[114:115], v[18:21], off offset:3072
; DI unsigned cvtpk(float lo, float hi) { unsigned r; asm volatile("v_cvt_pk_bf16_f32 %0, %1, %2" : "=v"(r) : "v"(lo), "v"(hi)); return r; }
; DI void rowwise(const PP& p, int l, int b, int mode, char* lds) {
;     ...
;         if (has_pre) {
;             float ss = 0.f;
; #pragma unroll
;             for (int j = 0; j < 4; ++j) ss += xv[j][0] * xv[j][0] + xv[j][1] * xv[j][1] + xv[j][2] * xv[j][2] + xv[j][3] * xv[j][3];
;             ss = wave_sum(ss);
;             const float rstd = rsqrtf(ss * (1.f / 1024.f) + 1e-6f);
;             f32x4 hv[4];
; #pragma unroll
;             for (int j = 0; j < 4; ++j) {
;                 const int c = j * 256 + lane * 4;
;                 const f32x4 g = *(const f32x4*)(gpre + c), sc = *(const f32x4*)(scp + c), sh = *(const f32x4*)(shp + c);
;                 hv[j] = xv[j] * rstd * g * (1.f + sc) + sh;
;                 u32x2 w = {cvtpk(hv[j][0], hv[j][1]), cvtpk(hv[j][2], hv[j][3])};
;                 *(u32x2*)(p.h + (size_t)row * 1024 + c) = w;
;             }
;             if (has_ff) {
;                 float f0 = 0, f1 = 0, f2 = 0, f3 = 0, f4 = 0, f5 = 0, f6 = 0, f7 = 0;
; #pragma unroll
;                 for (int j = 0; j < 4; ++j)
; #pragma unroll
;                     for (int e = 0; e < 4; ++e) {
;                         const int c = j * 256 + lane * 4 + e;
;                         const float* wr = wl + c * 8;
;                         const f32x4 w0 = *(const f32x4*)wr, w1 = *(const f32x4*)(wr + 4);
;                         const float hh = hv[j][e];
;                         f0 += hh * w0[0]; f1 += hh * w0[1]; f2 += hh * w0[2]; f3 += hh * w0[3];
;                         f4 += hh * w1[0]; f5 += hh * w1[1]; f6 += hh * w1[2]; f7 += hh * w1[3];
.LBB0_419:
	v_mul_f32_e32 v80, v31, v31
	v_mul_f32_e32 v81, v27, v27
	v_fmac_f32_e32 v80, v30, v30
	v_fmac_f32_e32 v81, v26, v26
	v_fmac_f32_e32 v80, v32, v32
	v_fmac_f32_e32 v81, v28, v28
	v_fmac_f32_e32 v80, v33, v33
	v_fmac_f32_e32 v81, v29, v29
	v_add_f32_e32 v80, v80, v81
	v_mul_f32_e32 v81, v23, v23
	v_fmac_f32_e32 v81, v22, v22
	v_fmac_f32_e32 v81, v24, v24
	v_fmac_f32_e32 v81, v25, v25
	v_add_f32_e32 v80, v81, v80
	v_mul_f32_e32 v81, v19, v19
	v_fmac_f32_e32 v81, v18, v18
	v_fmac_f32_e32 v81, v20, v20
	v_fmac_f32_e32 v81, v21, v21
	v_add_f32_e32 v80, v81, v80
	v_lshl_add_u64 v[102:103], v[70:71], 0, v[0:1]
	s_nop 0
	v_add_f32_dpp v80, v80, v80 quad_perm:[1,0,3,2] row_mask:0xf bank_mask:0xf bound_ctrl:1
	s_nop 1
	v_add_f32_dpp v80, v80, v80 quad_perm:[2,3,0,1] row_mask:0xf bank_mask:0xf bound_ctrl:1
	ds_swizzle_b32 v81, v80 offset:swizzle(SWAP,4)
	s_waitcnt lgkmcnt(0)
	v_add_f32_e32 v80, v80, v81
	ds_swizzle_b32 v81, v80 offset:swizzle(SWAP,8)
	s_waitcnt lgkmcnt(0)
	v_add_f32_e32 v80, v80, v81
	ds_swizzle_b32 v81, v80 offset:swizzle(SWAP,16)
	s_waitcnt lgkmcnt(0)
	v_add_f32_e32 v80, v80, v81
	v_mov_b32_e32 v81, v80
	s_nop 1
	v_permlane32_swap_b32_e32 v80, v81
	v_add_f32_e32 v80, v80, v81
	v_fmamk_f32 v80, v80, 0x3a800000, v217
	v_cmp_gt_f32_e32 vcc, s66, v80
	v_mul_f32_e32 v81, 0x4b800000, v80
	s_nop 0
	v_cndmask_b32_e32 v80, v80, v81, vcc
	v_rsq_f32_e32 v80, v80
	s_nop 0
	v_mul_f32_e32 v81, 0x45800000, v80
	v_cndmask_b32_e32 v80, v80, v81, vcc
	v_pk_mul_f32 v[32:33], v[32:33], v[80:81] op_sel_hi:[1,0]
	v_pk_mul_f32 v[30:31], v[30:31], v[80:81] op_sel_hi:[1,0]
	v_pk_mul_f32 v[28:29], v[28:29], v[80:81] op_sel_hi:[1,0]
	v_pk_mul_f32 v[26:27], v[26:27], v[80:81] op_sel_hi:[1,0]
	v_pk_mul_f32 v[24:25], v[24:25], v[80:81] op_sel_hi:[1,0]
	v_pk_mul_f32 v[22:23], v[22:23], v[80:81] op_sel_hi:[1,0]
	v_pk_mul_f32 v[20:21], v[20:21], v[80:81] op_sel_hi:[1,0]
	v_pk_mul_f32 v[18:19], v[18:19], v[80:81] op_sel_hi:[1,0]
	v_mov_b64_e32 v[82:83], v[158:159]
	v_mov_b64_e32 v[84:85], v[160:161]
	v_pk_mul_f32 v[82:83], v[82:83], v[30:31]
	v_pk_mul_f32 v[30:31], v[84:85], v[32:33]
	v_mov_b64_e32 v[86:87], v[162:163]
	v_mov_b64_e32 v[88:89], v[164:165]
	v_pk_add_f32 v[32:33], v[88:89], 1.0 op_sel_hi:[1,0]
	v_pk_add_f32 v[84:85], v[86:87], 1.0 op_sel_hi:[1,0]
	v_mov_b64_e32 v[94:95], v[166:167]
	v_mov_b64_e32 v[96:97], v[168:169]
	v_pk_fma_f32 v[30:31], v[32:33], v[30:31], v[96:97]
	v_pk_fma_f32 v[32:33], v[84:85], v[82:83], v[94:95]
	s_nop 0
	v_cvt_pk_bf16_f32 v82, v32, v33
	v_cvt_pk_bf16_f32 v83, v30, v31
	global_store_dwordx2 v[102:103], v[82:83], off
	s_nop 0
	v_mov_b64_e32 v[82:83], v[170:171]
	v_mov_b64_e32 v[84:85], v[172:173]
	v_pk_mul_f32 v[26:27], v[82:83], v[26:27]
	v_pk_mul_f32 v[28:29], v[84:85], v[28:29]
	v_mov_b64_e32 v[86:87], v[174:175]
	v_mov_b64_e32 v[88:89], v[176:177]
	v_pk_add_f32 v[82:83], v[88:89], 1.0 op_sel_hi:[1,0]
	v_pk_add_f32 v[84:85], v[86:87], 1.0 op_sel_hi:[1,0]
	v_mov_b64_e32 v[94:95], v[178:179]
	v_mov_b64_e32 v[96:97], v[180:181]
	v_pk_fma_f32 v[28:29], v[82:83], v[28:29], v[96:97]
	v_pk_fma_f32 v[82:83], v[84:85], v[26:27], v[94:95]
	s_nop 0
	v_cvt_pk_bf16_f32 v26, v82, v83
	v_cvt_pk_bf16_f32 v27, v28, v29
	global_store_dwordx2 v[102:103], v[26:27], off offset:512
	v_mov_b64_e32 v[84:85], v[182:183]
	v_mov_b64_e32 v[86:87], v[184:185]
	v_pk_mul_f32 v[26:27], v[22:23], v[84:85]
	v_pk_mul_f32 v[22:23], v[24:25], v[86:87]
	v_mov_b64_e32 v[94:95], v[186:187]
	v_mov_b64_e32 v[96:97], v[188:189]
	v_pk_add_f32 v[24:25], v[96:97], 1.0 op_sel_hi:[1,0]
	v_pk_add_f32 v[84:85], v[94:95], 1.0 op_sel_hi:[1,0]
	v_mov_b64_e32 v[98:99], v[190:191]
	v_mov_b64_e32 v[100:101], v[192:193]
	v_pk_fma_f32 v[22:23], v[22:23], v[24:25], v[100:101]
	v_pk_fma_f32 v[24:25], v[26:27], v[84:85], v[98:99]
	s_nop 0
	v_cvt_pk_bf16_f32 v26, v24, v25
	v_cvt_pk_bf16_f32 v27, v22, v23
	global_store_dwordx2 v[102:103], v[26:27], off offset:1024
	v_mov_b64_e32 v[84:85], v[194:195]
	v_mov_b64_e32 v[86:87], v[196:197]
	v_pk_mul_f32 v[18:19], v[18:19], v[84:85]
	v_pk_mul_f32 v[20:21], v[20:21], v[86:87]
	v_mov_b64_e32 v[94:95], v[198:199]
	v_mov_b64_e32 v[96:97], v[200:201]
	v_pk_add_f32 v[26:27], v[96:97], 1.0 op_sel_hi:[1,0]
	v_pk_add_f32 v[80:81], v[94:95], 1.0 op_sel_hi:[1,0]
	v_mov_b64_e32 v[98:99], v[202:203]
	v_mov_b64_e32 v[100:101], v[204:205]
	v_pk_fma_f32 v[26:27], v[20:21], v[26:27], v[100:101]
	v_pk_fma_f32 v[18:19], v[18:19], v[80:81], v[98:99]
	s_nop 0
	v_cvt_pk_bf16_f32 v20, v18, v19
	v_cvt_pk_bf16_f32 v21, v26, v27
	global_store_dwordx2 v[102:103], v[20:21], off offset:1536
	ds_read_b128 v[94:97], v35
	ds_read_b128 v[98:101], v35 offset:16
	ds_read_b128 v[102:105], v35 offset:32
	ds_read_b128 v[106:109], v35 offset:48
	s_waitcnt lgkmcnt(3)
	v_fma_f32 v87, v32, v94, 0
	v_fma_f32 v85, v32, v95, 0
	v_fma_f32 v81, v32, v96, 0
	v_fma_f32 v80, v32, v97, 0
	s_waitcnt lgkmcnt(2)
	v_fma_f32 v88, v32, v98, 0
	v_fma_f32 v86, v32, v99, 0
	v_fma_f32 v84, v32, v100, 0
	v_fma_f32 v32, v32, v101, 0
	ds_read_b128 v[94:97], v35 offset:64
	ds_read_b128 v[98:101], v35 offset:80
	s_waitcnt lgkmcnt(3)
	v_fmac_f32_e32 v87, v33, v102
	v_fmac_f32_e32 v85, v33, v103
	v_fmac_f32_e32 v81, v33, v104
	v_fmac_f32_e32 v80, v33, v105
	s_waitcnt lgkmcnt(2)
	v_fmac_f32_e32 v88, v33, v106
	v_fmac_f32_e32 v86, v33, v107
	v_fmac_f32_e32 v84, v33, v108
	v_fmac_f32_e32 v32, v33, v109
	s_waitcnt lgkmcnt(1)
	v_fmac_f32_e32 v87, v30, v94
	v_fmac_f32_e32 v85, v30, v95
	v_fmac_f32_e32 v81, v30, v96
	v_fmac_f32_e32 v80, v30, v97
	s_waitcnt lgkmcnt(0)
	v_fmac_f32_e32 v88, v30, v98
	v_fmac_f32_e32 v86, v30, v99
	v_fmac_f32_e32 v84, v30, v100
	v_fmac_f32_e32 v32, v30, v101
	ds_read_b128 v[94:97], v35 offset:96
	ds_read_b128 v[98:101], v35 offset:112
	s_waitcnt lgkmcnt(1)
; DI float shx1(float v) { return __int_as_float(__builtin_amdgcn_mov_dpp(__float_as_int(v), 0xB1, 0xf, 0xf, true)); }
; DI float shx2(float v) { return __int_as_float(__builtin_amdgcn_mov_dpp(__float_as_int(v), 0x4E, 0xf, 0xf, true)); }
; DI float shx4(float v) { return __int_as_float(__builtin_amdgcn_ds_swizzle(__float_as_int(v), 0x101f)); }
; DI float shx8(float v) { return __int_as_float(__builtin_amdgcn_ds_swizzle(__float_as_int(v), 0x201f)); }
; DI float shx16(float v) { return __int_as_float(__builtin_amdgcn_ds_swizzle(__float_as_int(v), 0x401f)); }
; #define RS32(a_, b_) ({ auto rr_ = __builtin_amdgcn_permlane32_swap(__float_as_uint(a_), __float_as_uint(b_), false, false); __uint_as_float(rr_[0]) + __uint_as_float(rr_[1]); })
; DI void rowwise(const PP& p, int l, int b, int mode, char* lds) {
;     ...
;                 float f0 = 0, f1 = 0, f2 = 0, f3 = 0, f4 = 0, f5 = 0, f6 = 0, f7 = 0;
; #pragma unroll
;                 for (int j = 0; j < 4; ++j)
; #pragma unroll
;                     for (int e = 0; e < 4; ++e) {
;                         const int c = j * 256 + lane * 4 + e;
;                         const float* wr = wl + c * 8;
;                         const f32x4 w0 = *(const f32x4*)wr, w1 = *(const f32x4*)(wr + 4);
;                         const float hh = hv[j][e];
;                         f0 += hh * w0[0]; f1 += hh * w0[1]; f2 += hh * w0[2]; f3 += hh * w0[3];
;                         f4 += hh * w1[0]; f5 += hh * w1[1]; f6 += hh * w1[2]; f7 += hh * w1[3];
;                     }
;     ...
;                 const float g0 = RS32(f0, f4), g1 = RS32(f1, f5), g2 = RS32(f2, f6), g3 = RS32(f3, f7);
;     ...
;                 const bool b4 = (lane & 16) != 0, b3 = (lane & 8) != 0;
;                 const float h0 = (b4 ? g2 : g0) + shx16(b4 ? g0 : g2), h1 = (b4 ? g3 : g1) + shx16(b4 ? g1 : g3);
;                 float z = (b3 ? h1 : h0) + shx8(b3 ? h0 : h1);
;                 z += shx4(z); z += shx2(z); z += shx1(z);
;                 if ((lane & 7) == 0) {
;                     z += p.b_f[l * 8 + (lane >> 3)];
;                     p.logf[(size_t)row * 8 + (lane >> 3)] = fminf(z, 0.f) - __logf(1.f + __expf(-fabsf(z)));
;                 }
	v_fmac_f32_e32 v87, v31, v94
	v_fmac_f32_e32 v85, v31, v95
	v_fmac_f32_e32 v81, v31, v96
	v_fmac_f32_e32 v80, v31, v97
	s_waitcnt lgkmcnt(0)
	v_fmac_f32_e32 v88, v31, v98
	v_fmac_f32_e32 v86, v31, v99
	v_fmac_f32_e32 v84, v31, v100
	v_fmac_f32_e32 v32, v31, v101
	ds_read_b128 v[94:97], v90
	ds_read_b128 v[98:101], v90 offset:16
	s_waitcnt lgkmcnt(1)
	v_fmac_f32_e32 v87, v82, v94
	v_fmac_f32_e32 v85, v82, v95
	v_fmac_f32_e32 v81, v82, v96
	v_fmac_f32_e32 v80, v82, v97
	s_waitcnt lgkmcnt(0)
	v_fmac_f32_e32 v88, v82, v98
	v_fmac_f32_e32 v86, v82, v99
	v_fmac_f32_e32 v84, v82, v100
	v_fmac_f32_e32 v32, v82, v101
	ds_read_b128 v[94:97], v35 offset:8224
	ds_read_b128 v[98:101], v35 offset:8240
	s_waitcnt lgkmcnt(1)
	v_fmac_f32_e32 v87, v83, v94
	v_fmac_f32_e32 v85, v83, v95
	v_fmac_f32_e32 v81, v83, v96
	v_fmac_f32_e32 v80, v83, v97
	s_waitcnt lgkmcnt(0)
	v_fmac_f32_e32 v88, v83, v98
	v_fmac_f32_e32 v86, v83, v99
	v_fmac_f32_e32 v84, v83, v100
	v_fmac_f32_e32 v32, v83, v101
	ds_read_b128 v[94:97], v35 offset:8256
	ds_read_b128 v[98:101], v35 offset:8272
	s_waitcnt lgkmcnt(1)
	v_fmac_f32_e32 v87, v28, v94
	v_fmac_f32_e32 v85, v28, v95
	v_fmac_f32_e32 v81, v28, v96
	v_fmac_f32_e32 v80, v28, v97
	s_waitcnt lgkmcnt(0)
	v_fmac_f32_e32 v88, v28, v98
	v_fmac_f32_e32 v86, v28, v99
	v_fmac_f32_e32 v84, v28, v100
	v_fmac_f32_e32 v32, v28, v101
	ds_read_b128 v[94:97], v35 offset:8288
	ds_read_b128 v[98:101], v35 offset:8304
	s_waitcnt lgkmcnt(1)
	v_fmac_f32_e32 v87, v29, v94
	v_fmac_f32_e32 v85, v29, v95
	v_fmac_f32_e32 v81, v29, v96
	v_fmac_f32_e32 v80, v29, v97
	s_waitcnt lgkmcnt(0)
	v_fmac_f32_e32 v88, v29, v98
	v_fmac_f32_e32 v86, v29, v99
	v_fmac_f32_e32 v84, v29, v100
	v_fmac_f32_e32 v32, v29, v101
	ds_read_b128 v[28:31], v91
	ds_read_b128 v[94:97], v91 offset:16
	s_waitcnt lgkmcnt(1)
	v_fmac_f32_e32 v87, v24, v28
	v_fmac_f32_e32 v85, v24, v29
	v_fmac_f32_e32 v81, v24, v30
	v_fmac_f32_e32 v80, v24, v31
	s_waitcnt lgkmcnt(0)
	v_fmac_f32_e32 v88, v24, v94
	v_fmac_f32_e32 v86, v24, v95
	v_fmac_f32_e32 v84, v24, v96
	v_fmac_f32_e32 v32, v24, v97
	ds_read_b128 v[28:31], v35 offset:16416
	ds_read_b128 v[94:97], v35 offset:16432
	s_waitcnt lgkmcnt(1)
	v_fmac_f32_e32 v87, v25, v28
	v_fmac_f32_e32 v85, v25, v29
	v_fmac_f32_e32 v81, v25, v30
	v_fmac_f32_e32 v80, v25, v31
	s_waitcnt lgkmcnt(0)
	v_fmac_f32_e32 v88, v25, v94
	v_fmac_f32_e32 v86, v25, v95
	v_fmac_f32_e32 v84, v25, v96
	v_fmac_f32_e32 v32, v25, v97
	ds_read_b128 v[28:31], v35 offset:16448
	ds_read_b128 v[94:97], v35 offset:16464
	s_waitcnt lgkmcnt(1)
	v_fmac_f32_e32 v87, v22, v28
	v_fmac_f32_e32 v85, v22, v29
	v_fmac_f32_e32 v81, v22, v30
	v_fmac_f32_e32 v80, v22, v31
	s_waitcnt lgkmcnt(0)
	v_fmac_f32_e32 v88, v22, v94
	v_fmac_f32_e32 v86, v22, v95
	v_fmac_f32_e32 v84, v22, v96
	v_fmac_f32_e32 v32, v22, v97
	ds_read_b128 v[28:31], v35 offset:16480
	ds_read_b128 v[94:97], v35 offset:16496
	s_waitcnt lgkmcnt(1)
	v_fmac_f32_e32 v87, v23, v28
	v_fmac_f32_e32 v85, v23, v29
	v_fmac_f32_e32 v81, v23, v30
	v_fmac_f32_e32 v80, v23, v31
	s_waitcnt lgkmcnt(0)
	v_fmac_f32_e32 v88, v23, v94
	v_fmac_f32_e32 v86, v23, v95
	v_fmac_f32_e32 v84, v23, v96
	v_fmac_f32_e32 v32, v23, v97
	ds_read_b128 v[20:23], v92
	ds_read_b128 v[28:31], v92 offset:16
	s_waitcnt lgkmcnt(1)
	v_fmac_f32_e32 v87, v18, v20
	v_fmac_f32_e32 v85, v18, v21
	v_fmac_f32_e32 v81, v18, v22
	v_fmac_f32_e32 v80, v18, v23
	s_waitcnt lgkmcnt(0)
	v_fmac_f32_e32 v88, v18, v28
	v_fmac_f32_e32 v86, v18, v29
	v_fmac_f32_e32 v84, v18, v30
	v_fmac_f32_e32 v32, v18, v31
	ds_read_b128 v[20:23], v35 offset:24608
	ds_read_b128 v[28:31], v35 offset:24624
	s_waitcnt lgkmcnt(1)
	v_fmac_f32_e32 v87, v19, v20
	v_fmac_f32_e32 v85, v19, v21
	v_fmac_f32_e32 v81, v19, v22
	v_fmac_f32_e32 v80, v19, v23
	s_waitcnt lgkmcnt(0)
	v_fmac_f32_e32 v88, v19, v28
	v_fmac_f32_e32 v86, v19, v29
	v_fmac_f32_e32 v84, v19, v30
	v_fmac_f32_e32 v32, v19, v31
	ds_read_b128 v[18:21], v35 offset:24640
	ds_read_b128 v[22:25], v35 offset:24656
	s_waitcnt lgkmcnt(1)
	v_fmac_f32_e32 v87, v26, v18
	v_fmac_f32_e32 v85, v26, v19
	v_fmac_f32_e32 v81, v26, v20
	v_fmac_f32_e32 v80, v26, v21
	s_waitcnt lgkmcnt(0)
	v_fmac_f32_e32 v88, v26, v22
	v_fmac_f32_e32 v86, v26, v23
	v_fmac_f32_e32 v84, v26, v24
	v_fmac_f32_e32 v32, v26, v25
	ds_read_b128 v[22:25], v35 offset:24672
	ds_read_b128 v[18:21], v35 offset:24688
	s_waitcnt lgkmcnt(1)
	v_fmac_f32_e32 v87, v27, v22
	v_fmac_f32_e32 v85, v27, v23
	v_fmac_f32_e32 v81, v27, v24
	v_fmac_f32_e32 v80, v27, v25
	s_waitcnt lgkmcnt(0)
	v_fmac_f32_e32 v88, v27, v18
	v_fmac_f32_e32 v86, v27, v19
	v_fmac_f32_e32 v84, v27, v20
	v_fmac_f32_e32 v32, v27, v21
	v_permlane32_swap_b32_e32 v87, v88
	v_permlane32_swap_b32_e32 v85, v86
	v_permlane32_swap_b32_e32 v81, v84
	v_permlane32_swap_b32_e32 v80, v32
	v_add_f32_e32 v18, v87, v88
	v_add_f32_e32 v19, v85, v86
	v_add_f32_e32 v20, v81, v84
	v_add_f32_e32 v21, v80, v32
	v_cndmask_b32_e64 v22, v20, v18, s[38:39]
	v_cndmask_b32_e64 v18, v18, v20, s[38:39]
	v_cndmask_b32_e64 v20, v21, v19, s[38:39]
	v_cndmask_b32_e64 v19, v19, v21, s[38:39]
	ds_swizzle_b32 v18, v18 offset:swizzle(SWAP,16)
	ds_swizzle_b32 v19, v19 offset:swizzle(SWAP,16)
	s_waitcnt lgkmcnt(1)
	v_add_f32_e32 v18, v22, v18
	s_waitcnt lgkmcnt(0)
	v_add_f32_e32 v19, v20, v19
	v_cndmask_b32_e64 v20, v19, v18, s[40:41]
	v_cndmask_b32_e64 v18, v18, v19, s[40:41]
	ds_swizzle_b32 v18, v18 offset:swizzle(SWAP,8)
	s_waitcnt lgkmcnt(0)
	v_add_f32_e32 v18, v20, v18
	ds_swizzle_b32 v19, v18 offset:swizzle(SWAP,4)
	s_waitcnt lgkmcnt(0)
	v_add_f32_e32 v18, v18, v19
	s_nop 1
	v_add_f32_dpp v18, v18, v18 quad_perm:[2,3,0,1] row_mask:0xf bank_mask:0xf bound_ctrl:1
	s_nop 1
	v_mov_b32_dpp v19, v18 quad_perm:[1,0,3,2] row_mask:0xf bank_mask:0xf bound_ctrl:1
	s_and_saveexec_b64 s[16:17], s[42:43]
	s_cbranch_execz .LBB0_410
	v_add_f32_e32 v18, v18, v19
	s_mov_b32 s0, 0xbfb8aa3b
	v_mov_b32_e32 v20, v146
	v_add_f32_e32 v18, v18, v20
	v_mul_f32_e64 v19, |v18|, s0
	v_exp_f32_e32 v19, v19
	s_mov_b32 s0, 0x3f317217
	v_min_f32_e32 v18, 0, v18
	v_add_f32_e32 v19, 1.0, v19
	v_cmp_gt_f32_e32 vcc, s66, v19
	s_nop 1
	v_cndmask_b32_e64 v20, 0, 32, vcc
	v_ldexp_f32 v19, v19, v20
	v_log_f32_e32 v19, v19
	s_nop 0
	v_mul_f32_e32 v20, 0x3f317217, v19
	v_fma_f32 v20, v19, s0, -v20
	v_fmac_f32_e32 v20, 0x3377d1cf, v19
	s_mov_b32 s0, 0x7f800000
	v_fmac_f32_e32 v20, 0x3f317217, v19
	v_cmp_lt_f32_e64 s[0:1], |v19|, s0
	s_nop 1
	v_cndmask_b32_e64 v19, v19, v20, s[0:1]
	v_mov_b32_e32 v20, 0x41b17218
	v_cndmask_b32_e32 v20, 0, v20, vcc
	v_sub_f32_e32 v19, v19, v20
	v_sub_f32_e32 v18, v18, v19
	global_store_dword v[68:69], v18, off
	s_branch .LBB0_410
